# overlap across segments: a[m] ds_bpermute broadcast of section m+1 issued at the start of section m (alternating spare registers), hiding the LDS round trip under the 32 VALU ops of the section
# speedup vs baseline: 1.0074x; 1.0074x over previous
.LBB0_324:
	s_nop 0
	v_readlane_b32 s0, v249, 46
	v_readlane_b32 s1, v249, 47
	s_and_b64 vcc, exec, s[0:1]
	s_cbranch_vccz .LBB0_345
	v_mov_b32_e32 v1, v220
	v_readlane_b32 s0, v249, 0
	s_nop 0
	v_ashrrev_i32_e32 v0, 6, v1
	v_lshl_add_u32 v116, s0, 2, v0
	s_movk_i32 s0, 0x4200
	v_cmp_gt_i32_e32 vcc, s0, v116
	s_and_saveexec_b64 s[0:1], vcc
	s_cbranch_execz .LBB0_344
	v_readlane_b32 s2, v249, 37
	v_readlane_b32 s26, v249, 30
	v_readlane_b32 s3, v249, 38
	v_readlane_b32 s27, v249, 31
	s_mul_hi_i32 s4, s2, 0x1400000
	s_mul_i32 s5, s2, 0x1400000
	s_load_dwordx2 s[2:3], s[26:27], 0x160
	v_and_b32_e32 v6, 31, v1
	v_mul_u32_u24_e32 v2, 24, v6
	v_mov_b32_e32 v3, v80
	v_and_b32_e32 v81, 63, v1
	v_and_b32_e32 v255, 32, v81
	v_lshlrev_b32_e32 v255, 2, v255
	s_waitcnt lgkmcnt(0)
	s_add_u32 s2, s2, s5
	s_addc_u32 s3, s3, s4
	v_lshl_add_u64 v[118:119], s[2:3], 0, v[2:3]
	v_lshlrev_b32_e32 v2, 4, v6
	s_getpc_b64 s[4:5]
	s_add_u32 s4, s4, c_cand@rel32@lo+4
	s_addc_u32 s5, s5, c_cand@rel32@hi+12
	v_lshl_add_u64 v[120:121], s[2:3], 0, v[2:3]
	s_load_dwordx4 s[12:15], s[26:27], 0x90
	s_load_dwordx2 s[2:3], s[26:27], 0xc8
	global_load_ubyte v2, v81, s[4:5]
	v_readlane_b32 s16, v249, 13
	s_sub_i32 s10, s16, 19
	s_cmp_lt_u32 s10, 6
	s_cselect_b64 s[4:5], -1, 0
	s_cmp_gt_u32 s10, 5
	v_readlane_b32 s10, v249, 39
	v_readlane_b32 s11, v249, 40
	s_cselect_b64 s[20:21], -1, 0
	s_lshl_b64 s[10:11], s[10:11], 2
	s_waitcnt lgkmcnt(0)
	s_add_u32 s22, s14, s10
	s_addc_u32 s23, s15, s11
	s_add_u32 s24, s12, s10
	s_addc_u32 s25, s13, s11
	s_load_dwordx2 s[10:11], s[26:27], 0x140
	v_lshlrev_b32_e32 v3, 3, v81
	v_lshlrev_b32_e32 v4, 6, v6
	v_mov_b32_e32 v5, v80
	v_lshl_or_b32 v239, v0, 12, v3
	s_waitcnt lgkmcnt(0)
	v_lshl_add_u64 v[122:123], s[10:11], 0, v[4:5]
	v_and_b32_e32 v3, 3, v1
	v_and_b32_e32 v4, 64, v229
	v_cmp_eq_u32_e64 s[12:13], 0, v3
	v_xor_b32_e32 v3, 4, v229
	v_add_u32_e32 v4, 64, v4
	v_cmp_lt_i32_e32 vcc, v3, v4
	v_readlane_b32 s18, v249, 15
	v_readlane_b32 s19, v249, 16
	v_cndmask_b32_e32 v3, v229, v3, vcc
	v_lshlrev_b32_e32 v240, 2, v3
	v_xor_b32_e32 v3, 8, v229
	v_cmp_lt_i32_e32 vcc, v3, v4
	v_readlane_b32 s17, v249, 14
	v_cmp_lt_u32_e64 s[6:7], 31, v81
	v_cndmask_b32_e32 v3, v229, v3, vcc
	v_lshlrev_b32_e32 v241, 2, v3
	v_xor_b32_e32 v3, 16, v229
	v_cmp_lt_i32_e32 vcc, v3, v4
	v_cmp_gt_u32_e64 s[8:9], 32, v81
	v_cmp_gt_u32_e64 s[10:11], 50, v81
	v_cndmask_b32_e32 v3, v229, v3, vcc
	v_lshlrev_b32_e32 v242, 2, v3
	v_xor_b32_e32 v3, 32, v229
	v_cmp_lt_i32_e32 vcc, v3, v4
	s_waitcnt vmcnt(0)
	v_and_b32_e32 v0, 15, v2
	v_cndmask_b32_e32 v3, v229, v3, vcc
	v_lshlrev_b32_e32 v243, 2, v3
	v_and_b32_e32 v3, 16, v1
	v_cmp_eq_u32_e64 s[14:15], 0, v3
	v_and_b32_e32 v3, 8, v1
	v_and_b32_e32 v1, 4, v1
	v_cmp_eq_u32_e64 s[18:19], 0, v1
	v_xor_b32_e32 v1, 2, v229
	v_cmp_lt_i32_e32 vcc, v1, v4
	v_lshrrev_b32_e32 v2, 4, v2
	v_cmp_eq_u32_e64 s[16:17], 0, v3
	v_cndmask_b32_e32 v1, v229, v1, vcc
	v_lshlrev_b32_e32 v244, 2, v1
	v_xor_b32_e32 v1, 1, v229
	v_cmp_lt_i32_e32 vcc, v1, v4
	v_lshlrev_b32_e32 v4, 7, v6
	v_lshl_add_u64 v[124:125], s[24:25], 0, v[4:5]
	v_cndmask_b32_e32 v1, v229, v1, vcc
	v_lshlrev_b32_e32 v245, 2, v1
	v_lshl_add_u64 v[126:127], s[22:23], 0, v[4:5]
	v_lshl_add_u64 v[128:129], s[2:3], 0, v[4:5]
	s_mov_b64 s[22:23], 0
	v_lshlrev_b32_e32 v130, 2, v2
	v_lshlrev_b32_e32 v132, 2, v0
	s_branch .LBB0_328

.LBB0_329:
	s_or_b64 exec, exec, s[2:3]
	v_mad_i64_i32 v[0:1], s[2:3], v0, s28, 0
	v_mad_i64_i32 v[4:5], s[2:3], v2, s28, 0
	v_mad_i64_i32 v[2:3], s[2:3], v3, s28, 0
	v_mad_i64_i32 v[8:9], s[2:3], v6, s28, 0
	v_mad_i64_i32 v[6:7], s[2:3], v7, s28, 0
	v_mad_i64_i32 v[12:13], s[2:3], v10, s28, 0
	v_mad_i64_i32 v[10:11], s[2:3], v11, s28, 0
	v_mad_i64_i32 v[14:15], s[2:3], v14, s28, 0
	s_brev_b32 s2, -2
	s_nop 0
	v_bfi_b32 v16, s2, v19, v16
	v_mul_f32_e32 v18, 0.5, v18
	v_add_f32_e32 v16, 1.0, v16
	v_mul_f32_e32 v16, v18, v16
	v_mul_f32_e32 v16, v17, v16
	v_mul_f32_e32 v117, 0x3daaaaab, v16
	ds_bpermute_b32 v250, v255, v117
	s_nop 0
	s_waitcnt vmcnt(23)
	v_cvt_scalef32_pk_f32_fp4 v[18:19], v110, 1.0
	s_waitcnt lgkmcnt(0)
	v_add_u32_e32 v254, 16, v255
	ds_bpermute_b32 v252, v254, v117
	v_cvt_scalef32_pk_f32_fp4 v[20:21], v110, 1.0 op_sel:[1,0,0]
	v_cvt_scalef32_pk_f32_fp4 v[22:23], v110, 1.0 op_sel:[0,1,0]
	v_cvt_scalef32_pk_f32_fp4 v[24:25], v110, 1.0 op_sel:[1,1,0]
	v_cvt_scalef32_pk_f32_fp4 v[26:27], v111, 1.0
	v_cvt_scalef32_pk_f32_fp4 v[28:29], v111, 1.0 op_sel:[1,0,0]
	v_cvt_scalef32_pk_f32_fp4 v[30:31], v111, 1.0 op_sel:[0,1,0]
	v_cvt_scalef32_pk_f32_fp4 v[110:111], v111, 1.0 op_sel:[1,1,0]
	v_pk_fma_f32 v[110:111], v[250:251], v[110:111], v[202:203] op_sel_hi:[0,1,1]
	v_cvt_scalef32_pk_f32_fp4 v[202:203], v112, 1.0
	v_pk_fma_f32 v[200:201], v[250:251], v[202:203], v[200:201] op_sel_hi:[0,1,1]
	v_cvt_scalef32_pk_f32_fp4 v[202:203], v112, 1.0 op_sel:[1,0,0]
	v_pk_fma_f32 v[198:199], v[250:251], v[202:203], v[198:199] op_sel_hi:[0,1,1]
	v_cvt_scalef32_pk_f32_fp4 v[202:203], v112, 1.0 op_sel:[0,1,0]
	v_pk_fma_f32 v[196:197], v[250:251], v[202:203], v[196:197] op_sel_hi:[0,1,1]
	v_cvt_scalef32_pk_f32_fp4 v[202:203], v112, 1.0 op_sel:[1,1,0]
	v_pk_fma_f32 v[194:195], v[250:251], v[202:203], v[194:195] op_sel_hi:[0,1,1]
	v_cvt_scalef32_pk_f32_fp4 v[202:203], v113, 1.0
	v_pk_fma_f32 v[192:193], v[250:251], v[202:203], v[192:193] op_sel_hi:[0,1,1]
	v_cvt_scalef32_pk_f32_fp4 v[202:203], v113, 1.0 op_sel:[1,0,0]
	v_pk_fma_f32 v[190:191], v[250:251], v[202:203], v[190:191] op_sel_hi:[0,1,1]
	v_cvt_scalef32_pk_f32_fp4 v[202:203], v113, 1.0 op_sel:[0,1,0]
	v_pk_fma_f32 v[188:189], v[250:251], v[202:203], v[188:189] op_sel_hi:[0,1,1]
	v_cvt_scalef32_pk_f32_fp4 v[112:113], v113, 1.0 op_sel:[1,1,0]
	v_pk_fma_f32 v[18:19], v[18:19], v[250:251], v[216:217] op_sel_hi:[1,0,1]
	v_pk_fma_f32 v[20:21], v[20:21], v[250:251], v[214:215] op_sel_hi:[1,0,1]
	v_pk_fma_f32 v[22:23], v[22:23], v[250:251], v[212:213] op_sel_hi:[1,0,1]
	v_pk_fma_f32 v[24:25], v[250:251], v[24:25], v[210:211] op_sel_hi:[0,1,1]
	v_pk_fma_f32 v[26:27], v[250:251], v[26:27], v[208:209] op_sel_hi:[0,1,1]
	v_pk_fma_f32 v[28:29], v[250:251], v[28:29], v[206:207] op_sel_hi:[0,1,1]
	v_pk_fma_f32 v[30:31], v[250:251], v[30:31], v[204:205] op_sel_hi:[0,1,1]
	v_pk_fma_f32 v[16:17], v[250:251], v[112:113], v[176:177] op_sel_hi:[0,1,1]
	s_waitcnt vmcnt(22)
	v_cvt_scalef32_pk_f32_fp4 v[176:177], v106, 1.0
	s_waitcnt lgkmcnt(0)
	v_add_u32_e32 v254, 32, v255
	ds_bpermute_b32 v250, v254, v117
	v_pk_fma_f32 v[18:19], v[176:177], v[252:253], v[18:19] op_sel_hi:[1,0,1]
	v_cvt_scalef32_pk_f32_fp4 v[176:177], v106, 1.0 op_sel:[1,0,0]
	v_pk_fma_f32 v[20:21], v[176:177], v[252:253], v[20:21] op_sel_hi:[1,0,1]
	v_cvt_scalef32_pk_f32_fp4 v[176:177], v106, 1.0 op_sel:[0,1,0]
	v_pk_fma_f32 v[22:23], v[176:177], v[252:253], v[22:23] op_sel_hi:[1,0,1]
	v_cvt_scalef32_pk_f32_fp4 v[176:177], v106, 1.0 op_sel:[1,1,0]
	v_pk_fma_f32 v[24:25], v[252:253], v[176:177], v[24:25] op_sel_hi:[0,1,1]
	v_cvt_scalef32_pk_f32_fp4 v[176:177], v107, 1.0
	v_pk_fma_f32 v[26:27], v[252:253], v[176:177], v[26:27] op_sel_hi:[0,1,1]
	v_cvt_scalef32_pk_f32_fp4 v[176:177], v107, 1.0 op_sel:[1,0,0]
	v_pk_fma_f32 v[28:29], v[252:253], v[176:177], v[28:29] op_sel_hi:[0,1,1]
	v_cvt_scalef32_pk_f32_fp4 v[176:177], v107, 1.0 op_sel:[0,1,0]
	v_pk_fma_f32 v[30:31], v[252:253], v[176:177], v[30:31] op_sel_hi:[0,1,1]
	v_cvt_scalef32_pk_f32_fp4 v[176:177], v108, 1.0 op_sel:[1,0,0]
	v_pk_fma_f32 v[176:177], v[252:253], v[176:177], v[198:199] op_sel_hi:[0,1,1]
	v_cvt_scalef32_pk_f32_fp4 v[198:199], v108, 1.0 op_sel:[0,1,0]
	v_pk_fma_f32 v[196:197], v[252:253], v[198:199], v[196:197] op_sel_hi:[0,1,1]
	v_cvt_scalef32_pk_f32_fp4 v[198:199], v108, 1.0 op_sel:[1,1,0]
	v_pk_fma_f32 v[194:195], v[252:253], v[198:199], v[194:195] op_sel_hi:[0,1,1]
	v_cvt_scalef32_pk_f32_fp4 v[198:199], v109, 1.0
	v_cvt_scalef32_pk_f32_fp4 v[106:107], v107, 1.0 op_sel:[1,1,0]
	v_pk_fma_f32 v[192:193], v[252:253], v[198:199], v[192:193] op_sel_hi:[0,1,1]
	v_cvt_scalef32_pk_f32_fp4 v[198:199], v109, 1.0 op_sel:[1,0,0]
	v_pk_fma_f32 v[106:107], v[252:253], v[106:107], v[110:111] op_sel_hi:[0,1,1]
	v_cvt_scalef32_pk_f32_fp4 v[110:111], v108, 1.0
	v_pk_fma_f32 v[190:191], v[252:253], v[198:199], v[190:191] op_sel_hi:[0,1,1]
	v_cvt_scalef32_pk_f32_fp4 v[198:199], v109, 1.0 op_sel:[0,1,0]
	v_pk_fma_f32 v[110:111], v[252:253], v[110:111], v[200:201] op_sel_hi:[0,1,1]
	v_pk_fma_f32 v[188:189], v[252:253], v[198:199], v[188:189] op_sel_hi:[0,1,1]
	v_cvt_scalef32_pk_f32_fp4 v[108:109], v109, 1.0 op_sel:[1,1,0]
	v_pk_fma_f32 v[16:17], v[252:253], v[108:109], v[16:17] op_sel_hi:[0,1,1]
	s_waitcnt vmcnt(21)
	v_cvt_scalef32_pk_f32_fp4 v[112:113], v102, 1.0
	s_waitcnt lgkmcnt(0)
	v_add_u32_e32 v254, 48, v255
	ds_bpermute_b32 v252, v254, v117
	v_pk_fma_f32 v[18:19], v[112:113], v[250:251], v[18:19] op_sel_hi:[1,0,1]
	v_cvt_scalef32_pk_f32_fp4 v[112:113], v102, 1.0 op_sel:[1,0,0]
	v_pk_fma_f32 v[20:21], v[112:113], v[250:251], v[20:21] op_sel_hi:[1,0,1]
	v_cvt_scalef32_pk_f32_fp4 v[112:113], v102, 1.0 op_sel:[0,1,0]
	v_pk_fma_f32 v[22:23], v[112:113], v[250:251], v[22:23] op_sel_hi:[1,0,1]
	v_cvt_scalef32_pk_f32_fp4 v[112:113], v102, 1.0 op_sel:[1,1,0]
	v_pk_fma_f32 v[24:25], v[250:251], v[112:113], v[24:25] op_sel_hi:[0,1,1]
	v_cvt_scalef32_pk_f32_fp4 v[112:113], v103, 1.0
	v_pk_fma_f32 v[26:27], v[250:251], v[112:113], v[26:27] op_sel_hi:[0,1,1]
	v_cvt_scalef32_pk_f32_fp4 v[112:113], v103, 1.0 op_sel:[1,0,0]
	v_pk_fma_f32 v[28:29], v[250:251], v[112:113], v[28:29] op_sel_hi:[0,1,1]
	v_cvt_scalef32_pk_f32_fp4 v[112:113], v103, 1.0 op_sel:[0,1,0]
	v_cvt_scalef32_pk_f32_fp4 v[102:103], v103, 1.0 op_sel:[1,1,0]
	v_pk_fma_f32 v[102:103], v[250:251], v[102:103], v[106:107] op_sel_hi:[0,1,1]
	v_cvt_scalef32_pk_f32_fp4 v[106:107], v104, 1.0
	v_pk_fma_f32 v[106:107], v[250:251], v[106:107], v[110:111] op_sel_hi:[0,1,1]
	v_cvt_scalef32_pk_f32_fp4 v[110:111], v104, 1.0 op_sel:[1,0,0]
	v_pk_fma_f32 v[110:111], v[250:251], v[110:111], v[176:177] op_sel_hi:[0,1,1]
	v_cvt_scalef32_pk_f32_fp4 v[176:177], v104, 1.0 op_sel:[1,1,0]
	v_pk_fma_f32 v[176:177], v[250:251], v[176:177], v[194:195] op_sel_hi:[0,1,1]
	v_cvt_scalef32_pk_f32_fp4 v[194:195], v105, 1.0
	v_pk_fma_f32 v[192:193], v[250:251], v[194:195], v[192:193] op_sel_hi:[0,1,1]
	v_cvt_scalef32_pk_f32_fp4 v[194:195], v105, 1.0 op_sel:[1,0,0]
	v_pk_fma_f32 v[30:31], v[250:251], v[112:113], v[30:31] op_sel_hi:[0,1,1]
	v_cvt_scalef32_pk_f32_fp4 v[112:113], v104, 1.0 op_sel:[0,1,0]
	v_pk_fma_f32 v[190:191], v[250:251], v[194:195], v[190:191] op_sel_hi:[0,1,1]
	v_cvt_scalef32_pk_f32_fp4 v[194:195], v105, 1.0 op_sel:[0,1,0]
	v_pk_fma_f32 v[112:113], v[250:251], v[112:113], v[196:197] op_sel_hi:[0,1,1]
	v_pk_fma_f32 v[188:189], v[250:251], v[194:195], v[188:189] op_sel_hi:[0,1,1]
	v_cvt_scalef32_pk_f32_fp4 v[104:105], v105, 1.0 op_sel:[1,1,0]
	v_pk_fma_f32 v[16:17], v[250:251], v[104:105], v[16:17] op_sel_hi:[0,1,1]
	s_waitcnt vmcnt(20)
	v_cvt_scalef32_pk_f32_fp4 v[108:109], v98, 1.0
	s_waitcnt lgkmcnt(0)
	v_add_u32_e32 v254, 64, v255
	ds_bpermute_b32 v250, v254, v117
	v_pk_fma_f32 v[18:19], v[108:109], v[252:253], v[18:19] op_sel_hi:[1,0,1]
	v_cvt_scalef32_pk_f32_fp4 v[108:109], v98, 1.0 op_sel:[1,0,0]
	v_pk_fma_f32 v[20:21], v[108:109], v[252:253], v[20:21] op_sel_hi:[1,0,1]
	v_cvt_scalef32_pk_f32_fp4 v[108:109], v98, 1.0 op_sel:[0,1,0]
	v_pk_fma_f32 v[22:23], v[108:109], v[252:253], v[22:23] op_sel_hi:[1,0,1]
	v_cvt_scalef32_pk_f32_fp4 v[108:109], v98, 1.0 op_sel:[1,1,0]
	v_pk_fma_f32 v[24:25], v[252:253], v[108:109], v[24:25] op_sel_hi:[0,1,1]
	v_cvt_scalef32_pk_f32_fp4 v[108:109], v99, 1.0
	v_pk_fma_f32 v[26:27], v[252:253], v[108:109], v[26:27] op_sel_hi:[0,1,1]
	v_cvt_scalef32_pk_f32_fp4 v[108:109], v99, 1.0 op_sel:[1,0,0]
	v_pk_fma_f32 v[28:29], v[252:253], v[108:109], v[28:29] op_sel_hi:[0,1,1]
	v_cvt_scalef32_pk_f32_fp4 v[108:109], v99, 1.0 op_sel:[0,1,0]
	v_cvt_scalef32_pk_f32_fp4 v[98:99], v99, 1.0 op_sel:[1,1,0]
	v_pk_fma_f32 v[98:99], v[252:253], v[98:99], v[102:103] op_sel_hi:[0,1,1]
	v_cvt_scalef32_pk_f32_fp4 v[102:103], v100, 1.0
	v_pk_fma_f32 v[102:103], v[252:253], v[102:103], v[106:107] op_sel_hi:[0,1,1]
	v_cvt_scalef32_pk_f32_fp4 v[106:107], v100, 1.0 op_sel:[1,0,0]
	v_pk_fma_f32 v[106:107], v[252:253], v[106:107], v[110:111] op_sel_hi:[0,1,1]
	v_cvt_scalef32_pk_f32_fp4 v[110:111], v100, 1.0 op_sel:[1,1,0]
	v_pk_fma_f32 v[30:31], v[252:253], v[108:109], v[30:31] op_sel_hi:[0,1,1]
	v_cvt_scalef32_pk_f32_fp4 v[108:109], v100, 1.0 op_sel:[0,1,0]
	v_pk_fma_f32 v[110:111], v[252:253], v[110:111], v[176:177] op_sel_hi:[0,1,1]
	v_cvt_scalef32_pk_f32_fp4 v[176:177], v101, 1.0 op_sel:[1,0,0]
	v_pk_fma_f32 v[108:109], v[252:253], v[108:109], v[112:113] op_sel_hi:[0,1,1]
	v_cvt_scalef32_pk_f32_fp4 v[112:113], v101, 1.0
	v_pk_fma_f32 v[176:177], v[252:253], v[176:177], v[190:191] op_sel_hi:[0,1,1]
	v_cvt_scalef32_pk_f32_fp4 v[190:191], v101, 1.0 op_sel:[0,1,0]
	v_pk_fma_f32 v[112:113], v[252:253], v[112:113], v[192:193] op_sel_hi:[0,1,1]
	v_pk_fma_f32 v[188:189], v[252:253], v[190:191], v[188:189] op_sel_hi:[0,1,1]
	v_cvt_scalef32_pk_f32_fp4 v[100:101], v101, 1.0 op_sel:[1,1,0]
	v_pk_fma_f32 v[16:17], v[252:253], v[100:101], v[16:17] op_sel_hi:[0,1,1]
	s_waitcnt vmcnt(19)
	v_cvt_scalef32_pk_f32_fp4 v[104:105], v94, 1.0
	s_waitcnt lgkmcnt(0)
	v_add_u32_e32 v254, 80, v255
	ds_bpermute_b32 v252, v254, v117
	v_pk_fma_f32 v[18:19], v[104:105], v[250:251], v[18:19] op_sel_hi:[1,0,1]
	v_cvt_scalef32_pk_f32_fp4 v[104:105], v94, 1.0 op_sel:[1,0,0]
	v_pk_fma_f32 v[20:21], v[104:105], v[250:251], v[20:21] op_sel_hi:[1,0,1]
	v_cvt_scalef32_pk_f32_fp4 v[104:105], v94, 1.0 op_sel:[0,1,0]
	v_pk_fma_f32 v[22:23], v[104:105], v[250:251], v[22:23] op_sel_hi:[1,0,1]
	v_cvt_scalef32_pk_f32_fp4 v[104:105], v94, 1.0 op_sel:[1,1,0]
	v_pk_fma_f32 v[24:25], v[250:251], v[104:105], v[24:25] op_sel_hi:[0,1,1]
	v_cvt_scalef32_pk_f32_fp4 v[104:105], v95, 1.0
	v_pk_fma_f32 v[26:27], v[250:251], v[104:105], v[26:27] op_sel_hi:[0,1,1]
	v_cvt_scalef32_pk_f32_fp4 v[104:105], v95, 1.0 op_sel:[1,0,0]
	v_pk_fma_f32 v[28:29], v[250:251], v[104:105], v[28:29] op_sel_hi:[0,1,1]
	v_cvt_scalef32_pk_f32_fp4 v[104:105], v95, 1.0 op_sel:[0,1,0]
	v_cvt_scalef32_pk_f32_fp4 v[94:95], v95, 1.0 op_sel:[1,1,0]
	v_pk_fma_f32 v[94:95], v[250:251], v[94:95], v[98:99] op_sel_hi:[0,1,1]
	v_cvt_scalef32_pk_f32_fp4 v[98:99], v96, 1.0
	v_pk_fma_f32 v[30:31], v[250:251], v[104:105], v[30:31] op_sel_hi:[0,1,1]
	v_pk_fma_f32 v[98:99], v[250:251], v[98:99], v[102:103] op_sel_hi:[0,1,1]
	v_cvt_scalef32_pk_f32_fp4 v[102:103], v96, 1.0 op_sel:[1,0,0]
	v_cvt_scalef32_pk_f32_fp4 v[104:105], v96, 1.0 op_sel:[0,1,0]
	v_pk_fma_f32 v[102:103], v[250:251], v[102:103], v[106:107] op_sel_hi:[0,1,1]
	v_pk_fma_f32 v[104:105], v[250:251], v[104:105], v[108:109] op_sel_hi:[0,1,1]
	v_cvt_scalef32_pk_f32_fp4 v[106:107], v96, 1.0 op_sel:[1,1,0]
	v_cvt_scalef32_pk_f32_fp4 v[108:109], v97, 1.0
	v_pk_fma_f32 v[106:107], v[250:251], v[106:107], v[110:111] op_sel_hi:[0,1,1]
	v_pk_fma_f32 v[108:109], v[250:251], v[108:109], v[112:113] op_sel_hi:[0,1,1]
	v_cvt_scalef32_pk_f32_fp4 v[110:111], v97, 1.0 op_sel:[1,0,0]
	v_cvt_scalef32_pk_f32_fp4 v[112:113], v97, 1.0 op_sel:[0,1,0]
	v_pk_fma_f32 v[110:111], v[250:251], v[110:111], v[176:177] op_sel_hi:[0,1,1]
	v_pk_fma_f32 v[112:113], v[250:251], v[112:113], v[188:189] op_sel_hi:[0,1,1]
	v_cvt_scalef32_pk_f32_fp4 v[96:97], v97, 1.0 op_sel:[1,1,0]
	v_pk_fma_f32 v[16:17], v[250:251], v[96:97], v[16:17] op_sel_hi:[0,1,1]
	s_waitcnt vmcnt(18)
	v_cvt_scalef32_pk_f32_fp4 v[100:101], v90, 1.0
	s_waitcnt lgkmcnt(0)
	v_add_u32_e32 v254, 96, v255
	ds_bpermute_b32 v250, v254, v117
	v_pk_fma_f32 v[18:19], v[100:101], v[252:253], v[18:19] op_sel_hi:[1,0,1]
	v_cvt_scalef32_pk_f32_fp4 v[100:101], v90, 1.0 op_sel:[1,0,0]
	v_pk_fma_f32 v[20:21], v[100:101], v[252:253], v[20:21] op_sel_hi:[1,0,1]
	v_cvt_scalef32_pk_f32_fp4 v[100:101], v90, 1.0 op_sel:[0,1,0]
	v_pk_fma_f32 v[22:23], v[100:101], v[252:253], v[22:23] op_sel_hi:[1,0,1]
	v_cvt_scalef32_pk_f32_fp4 v[100:101], v90, 1.0 op_sel:[1,1,0]
	v_pk_fma_f32 v[24:25], v[252:253], v[100:101], v[24:25] op_sel_hi:[0,1,1]
	v_cvt_scalef32_pk_f32_fp4 v[100:101], v91, 1.0
	v_pk_fma_f32 v[26:27], v[252:253], v[100:101], v[26:27] op_sel_hi:[0,1,1]
	v_cvt_scalef32_pk_f32_fp4 v[100:101], v91, 1.0 op_sel:[1,0,0]
	v_pk_fma_f32 v[28:29], v[252:253], v[100:101], v[28:29] op_sel_hi:[0,1,1]
	v_cvt_scalef32_pk_f32_fp4 v[100:101], v91, 1.0 op_sel:[0,1,0]
	v_cvt_scalef32_pk_f32_fp4 v[90:91], v91, 1.0 op_sel:[1,1,0]
	v_pk_fma_f32 v[90:91], v[252:253], v[90:91], v[94:95] op_sel_hi:[0,1,1]
	v_cvt_scalef32_pk_f32_fp4 v[94:95], v92, 1.0
	v_pk_fma_f32 v[30:31], v[252:253], v[100:101], v[30:31] op_sel_hi:[0,1,1]
	v_pk_fma_f32 v[94:95], v[252:253], v[94:95], v[98:99] op_sel_hi:[0,1,1]
	v_cvt_scalef32_pk_f32_fp4 v[98:99], v92, 1.0 op_sel:[1,0,0]
	v_cvt_scalef32_pk_f32_fp4 v[100:101], v92, 1.0 op_sel:[0,1,0]
	v_pk_fma_f32 v[98:99], v[252:253], v[98:99], v[102:103] op_sel_hi:[0,1,1]
	v_pk_fma_f32 v[100:101], v[252:253], v[100:101], v[104:105] op_sel_hi:[0,1,1]
	v_cvt_scalef32_pk_f32_fp4 v[102:103], v92, 1.0 op_sel:[1,1,0]
	v_cvt_scalef32_pk_f32_fp4 v[104:105], v93, 1.0
	v_pk_fma_f32 v[102:103], v[252:253], v[102:103], v[106:107] op_sel_hi:[0,1,1]
	v_pk_fma_f32 v[104:105], v[252:253], v[104:105], v[108:109] op_sel_hi:[0,1,1]
	v_cvt_scalef32_pk_f32_fp4 v[106:107], v93, 1.0 op_sel:[1,0,0]
	v_cvt_scalef32_pk_f32_fp4 v[108:109], v93, 1.0 op_sel:[0,1,0]
	v_pk_fma_f32 v[106:107], v[252:253], v[106:107], v[110:111] op_sel_hi:[0,1,1]
	v_pk_fma_f32 v[108:109], v[252:253], v[108:109], v[112:113] op_sel_hi:[0,1,1]
	v_cvt_scalef32_pk_f32_fp4 v[92:93], v93, 1.0 op_sel:[1,1,0]
	v_pk_fma_f32 v[16:17], v[252:253], v[92:93], v[16:17] op_sel_hi:[0,1,1]
	s_waitcnt vmcnt(17)
	v_cvt_scalef32_pk_f32_fp4 v[96:97], v86, 1.0
	s_waitcnt lgkmcnt(0)
	v_add_u32_e32 v254, 112, v255
	ds_bpermute_b32 v252, v254, v117
	v_pk_fma_f32 v[18:19], v[96:97], v[250:251], v[18:19] op_sel_hi:[1,0,1]
	v_cvt_scalef32_pk_f32_fp4 v[96:97], v86, 1.0 op_sel:[1,0,0]
	v_pk_fma_f32 v[20:21], v[96:97], v[250:251], v[20:21] op_sel_hi:[1,0,1]
	v_cvt_scalef32_pk_f32_fp4 v[96:97], v86, 1.0 op_sel:[0,1,0]
	v_pk_fma_f32 v[22:23], v[96:97], v[250:251], v[22:23] op_sel_hi:[1,0,1]
	v_cvt_scalef32_pk_f32_fp4 v[96:97], v86, 1.0 op_sel:[1,1,0]
	v_pk_fma_f32 v[24:25], v[250:251], v[96:97], v[24:25] op_sel_hi:[0,1,1]
	v_cvt_scalef32_pk_f32_fp4 v[96:97], v87, 1.0
	v_pk_fma_f32 v[26:27], v[250:251], v[96:97], v[26:27] op_sel_hi:[0,1,1]
	v_cvt_scalef32_pk_f32_fp4 v[96:97], v87, 1.0 op_sel:[1,0,0]
	v_pk_fma_f32 v[28:29], v[250:251], v[96:97], v[28:29] op_sel_hi:[0,1,1]
	v_cvt_scalef32_pk_f32_fp4 v[96:97], v87, 1.0 op_sel:[0,1,0]
	v_cvt_scalef32_pk_f32_fp4 v[86:87], v87, 1.0 op_sel:[1,1,0]
	v_pk_fma_f32 v[86:87], v[250:251], v[86:87], v[90:91] op_sel_hi:[0,1,1]
	v_cvt_scalef32_pk_f32_fp4 v[90:91], v88, 1.0
	v_pk_fma_f32 v[30:31], v[250:251], v[96:97], v[30:31] op_sel_hi:[0,1,1]
	v_pk_fma_f32 v[90:91], v[250:251], v[90:91], v[94:95] op_sel_hi:[0,1,1]
	v_cvt_scalef32_pk_f32_fp4 v[94:95], v88, 1.0 op_sel:[1,0,0]
	v_cvt_scalef32_pk_f32_fp4 v[96:97], v88, 1.0 op_sel:[0,1,0]
	v_pk_fma_f32 v[94:95], v[250:251], v[94:95], v[98:99] op_sel_hi:[0,1,1]
	v_pk_fma_f32 v[96:97], v[250:251], v[96:97], v[100:101] op_sel_hi:[0,1,1]
	v_cvt_scalef32_pk_f32_fp4 v[98:99], v88, 1.0 op_sel:[1,1,0]
	v_cvt_scalef32_pk_f32_fp4 v[100:101], v89, 1.0
	v_pk_fma_f32 v[98:99], v[250:251], v[98:99], v[102:103] op_sel_hi:[0,1,1]
	v_pk_fma_f32 v[100:101], v[250:251], v[100:101], v[104:105] op_sel_hi:[0,1,1]
	v_cvt_scalef32_pk_f32_fp4 v[102:103], v89, 1.0 op_sel:[1,0,0]
	v_cvt_scalef32_pk_f32_fp4 v[104:105], v89, 1.0 op_sel:[0,1,0]
	v_pk_fma_f32 v[102:103], v[250:251], v[102:103], v[106:107] op_sel_hi:[0,1,1]
	v_pk_fma_f32 v[104:105], v[250:251], v[104:105], v[108:109] op_sel_hi:[0,1,1]
	v_cvt_scalef32_pk_f32_fp4 v[88:89], v89, 1.0 op_sel:[1,1,0]
	v_pk_fma_f32 v[16:17], v[250:251], v[88:89], v[16:17] op_sel_hi:[0,1,1]
	s_waitcnt vmcnt(16)
	v_cvt_scalef32_pk_f32_fp4 v[92:93], v82, 1.0
	s_waitcnt lgkmcnt(0)
	v_pk_fma_f32 v[216:217], v[92:93], v[252:253], v[18:19] op_sel_hi:[1,0,1]
	v_cvt_scalef32_pk_f32_fp4 v[18:19], v82, 1.0 op_sel:[1,0,0]
	v_pk_fma_f32 v[214:215], v[18:19], v[252:253], v[20:21] op_sel_hi:[1,0,1]
	v_cvt_scalef32_pk_f32_fp4 v[18:19], v82, 1.0 op_sel:[0,1,0]
	v_pk_fma_f32 v[212:213], v[18:19], v[252:253], v[22:23] op_sel_hi:[1,0,1]
	v_cvt_scalef32_pk_f32_fp4 v[18:19], v82, 1.0 op_sel:[1,1,0]
	v_pk_fma_f32 v[210:211], v[252:253], v[18:19], v[24:25] op_sel_hi:[0,1,1]
	v_cvt_scalef32_pk_f32_fp4 v[18:19], v83, 1.0
	v_pk_fma_f32 v[208:209], v[252:253], v[18:19], v[26:27] op_sel_hi:[0,1,1]
	v_cvt_scalef32_pk_f32_fp4 v[18:19], v83, 1.0 op_sel:[1,0,0]
	v_pk_fma_f32 v[206:207], v[252:253], v[18:19], v[28:29] op_sel_hi:[0,1,1]
	v_cvt_scalef32_pk_f32_fp4 v[18:19], v83, 1.0 op_sel:[0,1,0]
	v_pk_fma_f32 v[204:205], v[252:253], v[18:19], v[30:31] op_sel_hi:[0,1,1]
	v_cvt_scalef32_pk_f32_fp4 v[18:19], v83, 1.0 op_sel:[1,1,0]
	v_pk_fma_f32 v[202:203], v[252:253], v[18:19], v[86:87] op_sel_hi:[0,1,1]
	v_cvt_scalef32_pk_f32_fp4 v[18:19], v84, 1.0
	v_pk_fma_f32 v[200:201], v[252:253], v[18:19], v[90:91] op_sel_hi:[0,1,1]
	v_cvt_scalef32_pk_f32_fp4 v[18:19], v84, 1.0 op_sel:[1,0,0]
	v_pk_fma_f32 v[198:199], v[252:253], v[18:19], v[94:95] op_sel_hi:[0,1,1]
	v_cvt_scalef32_pk_f32_fp4 v[18:19], v84, 1.0 op_sel:[0,1,0]
	v_pk_fma_f32 v[196:197], v[252:253], v[18:19], v[96:97] op_sel_hi:[0,1,1]
	v_cvt_scalef32_pk_f32_fp4 v[18:19], v84, 1.0 op_sel:[1,1,0]
	v_pk_fma_f32 v[194:195], v[252:253], v[18:19], v[98:99] op_sel_hi:[0,1,1]
	v_cvt_scalef32_pk_f32_fp4 v[18:19], v85, 1.0
	v_pk_fma_f32 v[192:193], v[252:253], v[18:19], v[100:101] op_sel_hi:[0,1,1]
	v_cvt_scalef32_pk_f32_fp4 v[18:19], v85, 1.0 op_sel:[1,0,0]
	v_pk_fma_f32 v[190:191], v[252:253], v[18:19], v[102:103] op_sel_hi:[0,1,1]
	v_cvt_scalef32_pk_f32_fp4 v[18:19], v85, 1.0 op_sel:[0,1,0]
	v_pk_fma_f32 v[188:189], v[252:253], v[18:19], v[104:105] op_sel_hi:[0,1,1]
	v_cvt_scalef32_pk_f32_fp4 v[18:19], v85, 1.0 op_sel:[1,1,0]
	v_pk_fma_f32 v[176:177], v[252:253], v[18:19], v[16:17] op_sel_hi:[0,1,1]
	v_lshl_add_u64 v[0:1], v[120:121], 0, v[0:1]
	v_lshl_add_u64 v[4:5], v[120:121], 0, v[4:5]
	global_load_dwordx4 v[110:113], v[0:1], off offset:768
	global_load_dwordx4 v[106:109], v[4:5], off offset:768
	v_lshl_add_u64 v[0:1], v[120:121], 0, v[2:3]
	v_lshl_add_u64 v[2:3], v[120:121], 0, v[8:9]
	global_load_dwordx4 v[102:105], v[0:1], off offset:768
	global_load_dwordx4 v[98:101], v[2:3], off offset:768
	v_lshl_add_u64 v[0:1], v[120:121], 0, v[6:7]
	v_lshl_add_u64 v[2:3], v[120:121], 0, v[12:13]
	global_load_dwordx4 v[94:97], v[0:1], off offset:768
	global_load_dwordx4 v[90:93], v[2:3], off offset:768
	v_lshl_add_u64 v[0:1], v[120:121], 0, v[10:11]
	v_lshl_add_u64 v[2:3], v[120:121], 0, v[14:15]
	global_load_dwordx4 v[86:89], v[0:1], off offset:768
	global_load_dwordx4 v[82:85], v[2:3], off offset:768
	s_addk_i32 s24, 0x200
	s_cmpk_lg_i32 s24, 0xe00
	s_cbranch_scc0 .LBB0_334
.LBB0_330:
	s_waitcnt vmcnt(22)
	v_cvt_scalef32_pk32_f32_fp6 v[0:31], v[32:37], 1.0
	v_pk_fma_f32 v[0:1], v[0:1], v[152:153], 0 op_sel_hi:[1,1,0]
	v_pk_fma_f32 v[2:3], v[2:3], v[170:171], 0 op_sel_hi:[1,1,0]
	v_pk_fma_f32 v[0:1], v[4:5], v[148:149], v[0:1]
	v_pk_fma_f32 v[2:3], v[6:7], v[172:173], v[2:3]
	v_pk_fma_f32 v[0:1], v[8:9], v[144:145], v[0:1]
	v_pk_fma_f32 v[2:3], v[10:11], v[174:175], v[2:3]
	v_pk_fma_f32 v[0:1], v[12:13], v[140:141], v[0:1]
	v_pk_fma_f32 v[2:3], v[14:15], v[178:179], v[2:3]
	v_pk_fma_f32 v[0:1], v[16:17], v[168:169], v[0:1]
	v_pk_fma_f32 v[2:3], v[18:19], v[180:181], v[2:3]
	v_pk_fma_f32 v[0:1], v[20:21], v[164:165], v[0:1]
	v_pk_fma_f32 v[2:3], v[22:23], v[182:183], v[2:3]
	v_pk_fma_f32 v[0:1], v[24:25], v[160:161], v[0:1]
	v_pk_fma_f32 v[2:3], v[26:27], v[184:185], v[2:3]
	v_pk_fma_f32 v[0:1], v[28:29], v[156:157], v[0:1]
	v_pk_fma_f32 v[2:3], v[30:31], v[186:187], v[2:3]
	v_add_f32_e32 v4, v2, v3
	v_add_f32_e32 v5, v0, v1
	v_add_f32_e32 v117, v4, v5
	s_waitcnt vmcnt(20)
	v_cvt_scalef32_pk32_f32_fp6 v[0:31], v[38:43], 1.0
	v_pk_fma_f32 v[0:1], v[0:1], v[152:153], 0 op_sel_hi:[1,1,0]
	v_pk_fma_f32 v[2:3], v[2:3], v[170:171], 0 op_sel_hi:[1,1,0]
	v_pk_fma_f32 v[0:1], v[4:5], v[148:149], v[0:1]
	v_pk_fma_f32 v[2:3], v[6:7], v[172:173], v[2:3]
	v_pk_fma_f32 v[0:1], v[8:9], v[144:145], v[0:1]
	v_pk_fma_f32 v[2:3], v[10:11], v[174:175], v[2:3]
	v_pk_fma_f32 v[0:1], v[12:13], v[140:141], v[0:1]
	v_pk_fma_f32 v[2:3], v[14:15], v[178:179], v[2:3]
	v_pk_fma_f32 v[0:1], v[16:17], v[168:169], v[0:1]
	v_pk_fma_f32 v[2:3], v[18:19], v[180:181], v[2:3]
	v_pk_fma_f32 v[0:1], v[20:21], v[164:165], v[0:1]
	v_pk_fma_f32 v[2:3], v[22:23], v[182:183], v[2:3]
	v_pk_fma_f32 v[0:1], v[24:25], v[160:161], v[0:1]
	v_pk_fma_f32 v[2:3], v[26:27], v[184:185], v[2:3]
	v_pk_fma_f32 v[0:1], v[28:29], v[156:157], v[0:1]
	v_pk_fma_f32 v[2:3], v[30:31], v[186:187], v[2:3]
	v_add_f32_e32 v4, v2, v3
	v_add_f32_e32 v5, v0, v1
	v_add_f32_e32 v131, v4, v5
	s_waitcnt vmcnt(18)
	v_cvt_scalef32_pk32_f32_fp6 v[0:31], v[44:49], 1.0
	v_pk_fma_f32 v[0:1], v[0:1], v[152:153], 0 op_sel_hi:[1,1,0]
	v_pk_fma_f32 v[2:3], v[2:3], v[170:171], 0 op_sel_hi:[1,1,0]
	v_pk_fma_f32 v[0:1], v[4:5], v[148:149], v[0:1]
	v_pk_fma_f32 v[2:3], v[6:7], v[172:173], v[2:3]
	v_pk_fma_f32 v[0:1], v[8:9], v[144:145], v[0:1]
	v_pk_fma_f32 v[2:3], v[10:11], v[174:175], v[2:3]
	v_pk_fma_f32 v[0:1], v[12:13], v[140:141], v[0:1]
	v_pk_fma_f32 v[2:3], v[14:15], v[178:179], v[2:3]
	v_pk_fma_f32 v[0:1], v[16:17], v[168:169], v[0:1]
	v_pk_fma_f32 v[2:3], v[18:19], v[180:181], v[2:3]
	v_pk_fma_f32 v[0:1], v[20:21], v[164:165], v[0:1]
	v_pk_fma_f32 v[2:3], v[22:23], v[182:183], v[2:3]
	v_pk_fma_f32 v[0:1], v[24:25], v[160:161], v[0:1]
	v_pk_fma_f32 v[2:3], v[26:27], v[184:185], v[2:3]
	v_pk_fma_f32 v[0:1], v[28:29], v[156:157], v[0:1]
	v_pk_fma_f32 v[2:3], v[30:31], v[186:187], v[2:3]
	v_add_f32_e32 v4, v2, v3
	v_add_f32_e32 v5, v0, v1
	v_add_f32_e32 v133, v4, v5
	s_waitcnt vmcnt(16)
	v_cvt_scalef32_pk32_f32_fp6 v[0:31], v[50:55], 1.0
	v_pk_fma_f32 v[0:1], v[0:1], v[152:153], 0 op_sel_hi:[1,1,0]
	v_pk_fma_f32 v[2:3], v[2:3], v[170:171], 0 op_sel_hi:[1,1,0]
	v_pk_fma_f32 v[0:1], v[4:5], v[148:149], v[0:1]
	v_pk_fma_f32 v[2:3], v[6:7], v[172:173], v[2:3]
	v_pk_fma_f32 v[0:1], v[8:9], v[144:145], v[0:1]
	v_pk_fma_f32 v[2:3], v[10:11], v[174:175], v[2:3]
	v_pk_fma_f32 v[0:1], v[12:13], v[140:141], v[0:1]
	v_pk_fma_f32 v[2:3], v[14:15], v[178:179], v[2:3]
	v_pk_fma_f32 v[0:1], v[16:17], v[168:169], v[0:1]
	v_pk_fma_f32 v[2:3], v[18:19], v[180:181], v[2:3]
	v_pk_fma_f32 v[0:1], v[20:21], v[164:165], v[0:1]
	v_pk_fma_f32 v[2:3], v[22:23], v[182:183], v[2:3]
	v_pk_fma_f32 v[0:1], v[24:25], v[160:161], v[0:1]
	v_pk_fma_f32 v[2:3], v[26:27], v[184:185], v[2:3]
	v_pk_fma_f32 v[0:1], v[28:29], v[156:157], v[0:1]
	v_pk_fma_f32 v[2:3], v[30:31], v[186:187], v[2:3]
	v_add_f32_e32 v4, v2, v3
	v_add_f32_e32 v5, v0, v1
	v_add_f32_e32 v218, v4, v5
	s_waitcnt vmcnt(14)
	v_cvt_scalef32_pk32_f32_fp6 v[0:31], v[56:61], 1.0
	v_pk_fma_f32 v[0:1], v[0:1], v[152:153], 0 op_sel_hi:[1,1,0]
	v_pk_fma_f32 v[2:3], v[2:3], v[170:171], 0 op_sel_hi:[1,1,0]
	v_pk_fma_f32 v[0:1], v[4:5], v[148:149], v[0:1]
	v_pk_fma_f32 v[2:3], v[6:7], v[172:173], v[2:3]
	v_pk_fma_f32 v[0:1], v[8:9], v[144:145], v[0:1]
	v_pk_fma_f32 v[2:3], v[10:11], v[174:175], v[2:3]
	v_pk_fma_f32 v[0:1], v[12:13], v[140:141], v[0:1]
	v_pk_fma_f32 v[2:3], v[14:15], v[178:179], v[2:3]
	v_pk_fma_f32 v[0:1], v[16:17], v[168:169], v[0:1]
	v_pk_fma_f32 v[2:3], v[18:19], v[180:181], v[2:3]
	v_pk_fma_f32 v[0:1], v[20:21], v[164:165], v[0:1]
	v_pk_fma_f32 v[2:3], v[22:23], v[182:183], v[2:3]
	v_pk_fma_f32 v[0:1], v[24:25], v[160:161], v[0:1]
	v_pk_fma_f32 v[2:3], v[26:27], v[184:185], v[2:3]
	v_pk_fma_f32 v[0:1], v[28:29], v[156:157], v[0:1]
	v_pk_fma_f32 v[2:3], v[30:31], v[186:187], v[2:3]
	v_add_f32_e32 v4, v2, v3
	v_add_f32_e32 v5, v0, v1
	v_add_f32_e32 v219, v4, v5
	s_waitcnt vmcnt(12)
	v_cvt_scalef32_pk32_f32_fp6 v[0:31], v[62:67], 1.0
	v_pk_fma_f32 v[0:1], v[0:1], v[152:153], 0 op_sel_hi:[1,1,0]
	v_pk_fma_f32 v[2:3], v[2:3], v[170:171], 0 op_sel_hi:[1,1,0]
	v_pk_fma_f32 v[0:1], v[4:5], v[148:149], v[0:1]
	v_pk_fma_f32 v[2:3], v[6:7], v[172:173], v[2:3]
	v_pk_fma_f32 v[0:1], v[8:9], v[144:145], v[0:1]
	v_pk_fma_f32 v[2:3], v[10:11], v[174:175], v[2:3]
	v_pk_fma_f32 v[0:1], v[12:13], v[140:141], v[0:1]
	v_pk_fma_f32 v[2:3], v[14:15], v[178:179], v[2:3]
	v_pk_fma_f32 v[0:1], v[16:17], v[168:169], v[0:1]
	v_pk_fma_f32 v[2:3], v[18:19], v[180:181], v[2:3]
	v_pk_fma_f32 v[0:1], v[20:21], v[164:165], v[0:1]
	v_pk_fma_f32 v[2:3], v[22:23], v[182:183], v[2:3]
	v_pk_fma_f32 v[0:1], v[24:25], v[160:161], v[0:1]
	v_pk_fma_f32 v[2:3], v[26:27], v[184:185], v[2:3]
	v_pk_fma_f32 v[0:1], v[28:29], v[156:157], v[0:1]
	v_pk_fma_f32 v[2:3], v[30:31], v[186:187], v[2:3]
	v_add_f32_e32 v4, v2, v3
	v_add_f32_e32 v5, v0, v1
	v_add_f32_e32 v246, v4, v5
	s_waitcnt vmcnt(10)
	v_cvt_scalef32_pk32_f32_fp6 v[0:31], v[68:73], 1.0
	v_pk_fma_f32 v[0:1], v[0:1], v[152:153], 0 op_sel_hi:[1,1,0]
	v_pk_fma_f32 v[2:3], v[2:3], v[170:171], 0 op_sel_hi:[1,1,0]
	v_pk_fma_f32 v[0:1], v[4:5], v[148:149], v[0:1]
	v_pk_fma_f32 v[2:3], v[6:7], v[172:173], v[2:3]
	v_pk_fma_f32 v[0:1], v[8:9], v[144:145], v[0:1]
	v_pk_fma_f32 v[2:3], v[10:11], v[174:175], v[2:3]
	v_pk_fma_f32 v[0:1], v[12:13], v[140:141], v[0:1]
	v_pk_fma_f32 v[2:3], v[14:15], v[178:179], v[2:3]
	v_pk_fma_f32 v[0:1], v[16:17], v[168:169], v[0:1]
	v_pk_fma_f32 v[2:3], v[18:19], v[180:181], v[2:3]
	v_pk_fma_f32 v[0:1], v[20:21], v[164:165], v[0:1]
	v_pk_fma_f32 v[2:3], v[22:23], v[182:183], v[2:3]
	v_pk_fma_f32 v[0:1], v[24:25], v[160:161], v[0:1]
	v_pk_fma_f32 v[2:3], v[26:27], v[184:185], v[2:3]
	v_pk_fma_f32 v[0:1], v[28:29], v[156:157], v[0:1]
	v_pk_fma_f32 v[2:3], v[30:31], v[186:187], v[2:3]
	v_add_f32_e32 v4, v2, v3
	v_add_f32_e32 v5, v0, v1
	v_add_f32_e32 v247, v4, v5
	s_waitcnt vmcnt(8)
	v_cvt_scalef32_pk32_f32_fp6 v[0:31], v[74:79], 1.0
	v_pk_fma_f32 v[0:1], v[0:1], v[152:153], 0 op_sel_hi:[1,1,0]
	v_pk_fma_f32 v[2:3], v[2:3], v[170:171], 0 op_sel_hi:[1,1,0]
	v_pk_fma_f32 v[0:1], v[4:5], v[148:149], v[0:1]
	v_pk_fma_f32 v[2:3], v[6:7], v[172:173], v[2:3]
	v_pk_fma_f32 v[0:1], v[8:9], v[144:145], v[0:1]
	v_pk_fma_f32 v[2:3], v[10:11], v[174:175], v[2:3]
	v_pk_fma_f32 v[0:1], v[12:13], v[140:141], v[0:1]
	v_pk_fma_f32 v[2:3], v[14:15], v[178:179], v[2:3]
	v_pk_fma_f32 v[0:1], v[16:17], v[168:169], v[0:1]
	v_pk_fma_f32 v[2:3], v[18:19], v[180:181], v[2:3]
	v_pk_fma_f32 v[0:1], v[20:21], v[164:165], v[0:1]
	v_pk_fma_f32 v[2:3], v[22:23], v[182:183], v[2:3]
	v_pk_fma_f32 v[0:1], v[24:25], v[160:161], v[0:1]
	v_pk_fma_f32 v[2:3], v[26:27], v[184:185], v[2:3]
	v_pk_fma_f32 v[0:1], v[28:29], v[156:157], v[0:1]
	v_pk_fma_f32 v[2:3], v[30:31], v[186:187], v[2:3]
	v_add_f32_e32 v4, v2, v3
	v_add_f32_e32 v5, v0, v1
	v_add_f32_e32 v1, v4, v5
	v_add_u32_e32 v8, s24, v239
	ds_read_b32 v12, v8 offset:512
	s_waitcnt lgkmcnt(0)
	v_add_u32_e32 v13, 0, v255
	v_add_u32_e32 v15, 16, v255
	v_add_u32_e32 v18, 32, v255
	v_add_u32_e32 v19, 48, v255
	v_add_u32_e32 v20, 64, v255
	v_add_u32_e32 v21, 80, v255
	v_add_u32_e32 v26, 96, v255
	v_add_u32_e32 v27, 112, v255
	ds_bpermute_b32 v0, v13, v12
	ds_bpermute_b32 v2, v15, v12
	ds_bpermute_b32 v3, v18, v12
	ds_bpermute_b32 v6, v19, v12
	ds_bpermute_b32 v7, v20, v12
	ds_bpermute_b32 v10, v21, v12
	ds_bpermute_b32 v11, v26, v12
	ds_bpermute_b32 v14, v27, v12
	s_waitcnt lgkmcnt(7)
	v_mad_i64_i32 v[22:23], s[2:3], v0, s28, v[118:119]
	global_load_dwordx2 v[36:37], v[22:23], off offset:16
	global_load_dwordx4 v[32:35], v[22:23], off
	s_waitcnt lgkmcnt(6)
	v_mad_i64_i32 v[24:25], s[2:3], v2, s28, v[118:119]
	global_load_dwordx2 v[42:43], v[24:25], off offset:16
	global_load_dwordx4 v[38:41], v[24:25], off
	s_waitcnt lgkmcnt(5)
	v_mad_i64_i32 v[22:23], s[2:3], v3, s28, v[118:119]
	global_load_dwordx2 v[48:49], v[22:23], off offset:16
	global_load_dwordx4 v[44:47], v[22:23], off
	s_waitcnt lgkmcnt(4)
	v_mad_i64_i32 v[24:25], s[2:3], v6, s28, v[118:119]
	global_load_dwordx2 v[54:55], v[24:25], off offset:16
	global_load_dwordx4 v[50:53], v[24:25], off
	s_waitcnt lgkmcnt(3)
	v_mad_i64_i32 v[22:23], s[2:3], v7, s28, v[118:119]
	global_load_dwordx2 v[60:61], v[22:23], off offset:16
	global_load_dwordx4 v[56:59], v[22:23], off
	s_waitcnt lgkmcnt(2)
	v_mad_i64_i32 v[24:25], s[2:3], v10, s28, v[118:119]
	global_load_dwordx2 v[66:67], v[24:25], off offset:16
	global_load_dwordx4 v[62:65], v[24:25], off
	s_waitcnt lgkmcnt(1)
	v_mad_i64_i32 v[22:23], s[2:3], v11, s28, v[118:119]
	global_load_dwordx2 v[72:73], v[22:23], off offset:16
	global_load_dwordx4 v[68:71], v[22:23], off
	s_waitcnt lgkmcnt(0)
	v_mad_i64_i32 v[24:25], s[2:3], v14, s28, v[118:119]
	global_load_dwordx2 v[78:79], v[24:25], off offset:16
	global_load_dwordx4 v[74:77], v[24:25], off
	ds_read_b64 v[16:17], v8
	v_cndmask_b32_e64 v4, v117, v219, s[14:15]
	ds_bpermute_b32 v4, v242, v4
	v_cndmask_b32_e64 v5, v219, v117, s[14:15]
	v_cndmask_b32_e64 v8, v131, v246, s[14:15]
	ds_bpermute_b32 v8, v242, v8
	v_cndmask_b32_e64 v12, v218, v1, s[14:15]
	s_waitcnt lgkmcnt(1)
	v_add_f32_e32 v4, v5, v4
	v_cndmask_b32_e64 v5, v133, v247, s[14:15]
	ds_bpermute_b32 v5, v242, v5
	ds_bpermute_b32 v12, v242, v12
	v_cndmask_b32_e64 v9, v246, v131, s[14:15]
	s_waitcnt lgkmcnt(2)
	v_add_f32_e32 v8, v9, v8
	v_cndmask_b32_e64 v9, v247, v133, s[14:15]
	v_cndmask_b32_e64 v1, v1, v218, s[14:15]
	s_waitcnt lgkmcnt(1)
	v_add_f32_e32 v5, v9, v5
	s_waitcnt lgkmcnt(0)
	v_add_f32_e32 v1, v1, v12
	v_cndmask_b32_e64 v9, v4, v5, s[16:17]
	v_cndmask_b32_e64 v12, v8, v1, s[16:17]
	ds_bpermute_b32 v9, v241, v9
	ds_bpermute_b32 v12, v241, v12
	v_cndmask_b32_e64 v4, v5, v4, s[16:17]
	v_cndmask_b32_e64 v1, v1, v8, s[16:17]
	s_waitcnt lgkmcnt(1)
	v_add_f32_e32 v4, v4, v9
	s_waitcnt lgkmcnt(0)
	v_add_f32_e32 v1, v1, v12
	v_cndmask_b32_e64 v5, v4, v1, s[18:19]
	ds_bpermute_b32 v5, v240, v5
	v_cndmask_b32_e64 v1, v1, v4, s[18:19]
	s_waitcnt lgkmcnt(0)
	v_add_f32_e32 v1, v1, v5
	ds_bpermute_b32 v4, v244, v1
	s_waitcnt lgkmcnt(0)
	v_add_f32_e32 v1, v1, v4
	ds_bpermute_b32 v4, v245, v1
	s_waitcnt lgkmcnt(0)
	v_add_f32_e32 v1, v1, v4
	v_mul_f32_e32 v18, 0x3caaaaab, v1
	v_mul_f32_e32 v16, 0x3f3504f3, v18
	v_cmp_nlt_f32_e64 s[2:3], |v16|, 1.0
	s_and_saveexec_b64 s[26:27], s[2:3]
	s_xor_b64 s[2:3], exec, s[26:27]
	s_cbranch_execz .LBB0_332
	s_mov_b32 s25, 0x378e98ab
	v_fma_f32 v1, |v16|, s25, v233
	s_mov_b32 s25, 0x3b7cd369
	v_fma_f32 v1, |v16|, v1, s25
	s_mov_b32 s25, 0xbcc618b2
	v_fma_f32 v1, |v16|, v1, s25
	s_mov_b32 s25, 0x3dda74e4
	v_fma_f32 v1, |v16|, v1, s25
	s_mov_b32 s25, 0x3f228afd
	v_fma_f32 v1, |v16|, v1, s25
	s_mov_b32 s25, 0x3e03c728
	v_fma_f32 v1, |v16|, v1, s25
	v_fma_f32 v1, |v16|, v1, |v16|
	v_mul_f32_e32 v4, 0xbfb8aa3b, v1
	s_mov_b32 s25, 0xbfb8aa3b
	v_fma_f32 v5, v1, s25, -v4
	v_rndne_f32_e32 v8, v4
	v_fmac_f32_e32 v5, 0xb2a5705f, v1
	v_sub_f32_e32 v4, v4, v8
	v_add_f32_e32 v4, v4, v5
	v_cvt_i32_f32_e32 v5, v8
	v_exp_f32_e32 v4, v4
	s_mov_b32 s25, 0x42ce8ed0
	v_cmp_nlt_f32_e32 vcc, s25, v1
	s_mov_b32 s25, 0xc2b17218
	v_ldexp_f32 v4, v4, v5
	v_cndmask_b32_e32 v4, 0, v4, vcc
	v_cmp_ngt_f32_e32 vcc, s25, v1
	s_nop 1
	v_cndmask_b32_e32 v1, v234, v4, vcc
	v_sub_f32_e32 v19, 1.0, v1
